# gates buffer in 16-row x 32-col 1 KB blocks: in-proj sigmoid-tile stores and gated-merge epilogue gate loads are 1 KB contiguous per wave instruction
# baseline (speedup 1.0000x reference)
; __device__ __forceinline__ u32x4 pack8(const f32x4 a, const f32x4 b) { u32x4 w; w.x = cvt_pk_bf16(a[0], a[1]); w.y = cvt_pk_bf16(a[2], a[3]); w.z = cvt_pk_bf16(b[0], b[1]); w.w = cvt_pk_bf16(b[2], b[3]); return w; }
; __device__ __forceinline__ f32x4 sigm4(const f32x4 v) { f32x4 o; o[0] = sigm(v[0]); o[1] = sigm(v[1]); o[2] = sigm(v[2]); o[3] = sigm(v[3]); return o; }
; #define EPI_ROWLOOP _Pragma("unroll") for (int ai = 0; ai < 2; ++ai) _Pragma("unroll") for (int m = 0; m < 4; ++m)
;     __device__ __forceinline__ void operator()(const f32x4 (&acc)[2][2][4][2], const Unit& u, int wr, int wc, int fr, int fq) const {
;     ...
;             if (u.pm * BM >= EP_MR) return;
;             const int gc = (pn - 18) * 256 + cl;
;             f32x4 bv[2][2];
; #pragma unroll
;             for (int bj = 0; bj < 2; ++bj) { bv[bj][0] = *(const f32x4*)(b_gate + gc + bj * HALF); bv[bj][1] = *(const f32x4*)(b_gate + gc + bj * HALF + 4); }
;             EPI_ROWLOOP { bf16_t* rowp = GATES + (size_t)(row0 + ai * HALF + m * 16) * 2048 + gc;
; #pragma unroll
;                 for (int bj = 0; bj < 2; ++bj) *(u32x4*)(rowp + bj * HALF) = pack8(sigm4(acc[ai][bj][m][0] + bv[bj][0]), sigm4(acc[ai][bj][m][1] + bv[bj][1])); }
.LBB0_259:
	s_andn2_b64 vcc, exec, s[0:1]
	s_cbranch_vccnz .LBB0_262
	s_cmpk_gt_i32 s48, 0xff
	s_cbranch_scc1 .LBB0_262
	v_lshl_add_u32 v170, s49, 8, v177
	v_mov_b32_e32 v171, v0
	v_lshl_add_u64 v[134:135], v[170:171], 2, s[42:43]
	global_load_dwordx4 v[138:141], v[134:135], off offset:16
	global_load_dwordx4 v[142:145], v[134:135], off
	global_load_dwordx4 v[130:133], v[134:135], off offset:528
	s_nop 0
	global_load_dwordx4 v[134:137], v[134:135], off offset:512
	v_and_b32_e32 v196, 15, v168
	v_and_b32_e32 v168, -16, v168
	v_ashrrev_i32_e32 v169, 31, v168
	v_lshlrev_b64 v[172:173], 12, v[168:169]
	v_lshl_add_u64 v[174:175], s[26:27], 0, v[172:173]
	v_lshrrev_b32_e32 v197, 8, v170
	v_lshlrev_b32_e32 v172, 13, v197
	v_bfe_u32 v197, v170, 5, 2
	v_lshl_or_b32 v172, v197, 11, v172
	v_and_b32_e32 v197, 31, v170
	v_lshl_or_b32 v172, v197, 1, v172
	v_lshl_or_b32 v172, v196, 6, v172
	v_mov_b32_e32 v173, 0
	v_lshl_add_u64 v[170:171], v[174:175], 0, v[172:173]
	s_mov_b64 s[0:1], 0x80000
	s_waitcnt vmcnt(0)
	v_pk_add_f32 v[174:175], v[128:129], v[144:145]
	s_nop 0
	v_mul_f32_e32 v174, 0xbfb8aa3b, v174
	v_exp_f32_e32 v174, v174
	v_pk_add_f32 v[182:183], v[126:127], v[142:143]
	v_add_f32_e32 v174, 1.0, v174
	v_rcp_f32_e32 v184, v174
	v_mul_f32_e32 v174, 0xbfb8aa3b, v175
	v_exp_f32_e32 v174, v174
	v_mul_f32_e32 v1, 0xbfb8aa3b, v182
	v_mul_f32_e32 v169, 0xbfb8aa3b, v183
	v_pk_add_f32 v[182:183], v[122:123], v[138:139]
	v_add_f32_e32 v174, 1.0, v174
	v_rcp_f32_e32 v185, v174
	v_pk_add_f32 v[174:175], v[124:125], v[140:141]
	v_mul_f32_e32 v182, 0xbfb8aa3b, v182
	v_exp_f32_e32 v182, v182
	v_mul_f32_e32 v174, 0xbfb8aa3b, v174
	v_mul_f32_e32 v175, 0xbfb8aa3b, v175
	v_exp_f32_e32 v174, v174
	v_exp_f32_e32 v175, v175
	v_add_f32_e32 v182, 1.0, v182
	v_rcp_f32_e32 v186, v182
	v_mul_f32_e32 v182, 0xbfb8aa3b, v183
	v_add_f32_e32 v174, 1.0, v174
	v_add_f32_e32 v175, 1.0, v175
	v_exp_f32_e32 v1, v1
	v_exp_f32_e32 v169, v169
	v_exp_f32_e32 v182, v182
	v_rcp_f32_e32 v174, v174
	v_rcp_f32_e32 v175, v175
	v_add_f32_e32 v1, 1.0, v1
	v_add_f32_e32 v169, 1.0, v169
	v_add_f32_e32 v182, 1.0, v182
	v_cvt_pk_bf16_f32 v183, v184, v185
	v_cvt_pk_bf16_f32 v185, v174, v175
	v_pk_add_f32 v[174:175], v[120:121], v[136:137]
	v_rcp_f32_e32 v1, v1
	v_rcp_f32_e32 v169, v169
	v_rcp_f32_e32 v187, v182
	v_mul_f32_e32 v174, 0xbfb8aa3b, v174
	v_exp_f32_e32 v174, v174
	v_cvt_pk_bf16_f32 v182, v1, v169
	v_cvt_pk_bf16_f32 v184, v186, v187
	global_store_dwordx4 v[170:171], v[182:185], off nt
	v_add_f32_e32 v174, 1.0, v174
	s_nop 0
	v_pk_add_f32 v[182:183], v[118:119], v[134:135]
	v_rcp_f32_e32 v184, v174
	v_mul_f32_e32 v1, 0xbfb8aa3b, v182
	v_mul_f32_e32 v169, 0xbfb8aa3b, v183
	v_mul_f32_e32 v174, 0xbfb8aa3b, v175
	v_pk_add_f32 v[182:183], v[114:115], v[130:131]
	v_exp_f32_e32 v174, v174
	v_mul_f32_e32 v182, 0xbfb8aa3b, v182
	v_exp_f32_e32 v182, v182
	v_exp_f32_e32 v1, v1
	v_add_f32_e32 v174, 1.0, v174
	v_rcp_f32_e32 v185, v174
	v_pk_add_f32 v[174:175], v[116:117], v[132:133]
	v_add_f32_e32 v182, 1.0, v182
	v_rcp_f32_e32 v186, v182
	v_mul_f32_e32 v182, 0xbfb8aa3b, v183
	v_mul_f32_e32 v174, 0xbfb8aa3b, v174
	v_mul_f32_e32 v175, 0xbfb8aa3b, v175
	v_exp_f32_e32 v169, v169
	v_exp_f32_e32 v182, v182
	v_exp_f32_e32 v174, v174
	v_exp_f32_e32 v175, v175
	v_add_f32_e32 v1, 1.0, v1
	v_add_f32_e32 v169, 1.0, v169
	v_add_f32_e32 v182, 1.0, v182
	v_add_f32_e32 v174, 1.0, v174
	v_add_f32_e32 v175, 1.0, v175
	v_rcp_f32_e32 v1, v1
	v_rcp_f32_e32 v169, v169
	v_rcp_f32_e32 v187, v182
	v_rcp_f32_e32 v174, v174
	v_rcp_f32_e32 v175, v175
	v_cvt_pk_bf16_f32 v182, v1, v169
	v_cvt_pk_bf16_f32 v183, v184, v185
	v_cvt_pk_bf16_f32 v184, v186, v187
	v_cvt_pk_bf16_f32 v185, v174, v175
	global_store_dwordx4 v[170:171], v[182:185], off offset:1024 nt
	v_or_b32_e32 v174, 16, v168
	v_ashrrev_i32_e32 v175, 31, v174
	v_pk_add_f32 v[182:183], v[112:113], v[144:145]
	v_pk_add_f32 v[184:185], v[110:111], v[142:143]
	v_mul_f32_e32 v182, 0xbfb8aa3b, v182
	v_exp_f32_e32 v182, v182
	v_mul_f32_e32 v1, 0xbfb8aa3b, v184
	v_mul_f32_e32 v169, 0xbfb8aa3b, v185
	v_pk_add_f32 v[184:185], v[106:107], v[138:139]
	v_add_f32_e32 v182, 1.0, v182
	v_rcp_f32_e32 v186, v182
	v_mul_f32_e32 v182, 0xbfb8aa3b, v183
	v_exp_f32_e32 v182, v182
	v_mul_f32_e32 v184, 0xbfb8aa3b, v184
	v_mul_f32_e32 v185, 0xbfb8aa3b, v185
	v_exp_f32_e32 v1, v1
	v_add_f32_e32 v182, 1.0, v182
	v_rcp_f32_e32 v187, v182
	v_pk_add_f32 v[182:183], v[108:109], v[140:141]
	v_exp_f32_e32 v169, v169
	v_mul_f32_e32 v182, 0xbfb8aa3b, v182
	v_exp_f32_e32 v182, v182
	v_exp_f32_e32 v184, v184
	v_exp_f32_e32 v185, v185
	v_add_f32_e32 v1, 1.0, v1
	v_add_f32_e32 v182, 1.0, v182
	v_rcp_f32_e32 v188, v182
	v_mul_f32_e32 v182, 0xbfb8aa3b, v183
	v_exp_f32_e32 v182, v182
	v_add_f32_e32 v169, 1.0, v169
	v_add_f32_e32 v184, 1.0, v184
	v_add_f32_e32 v185, 1.0, v185
	v_add_f32_e32 v182, 1.0, v182
	v_rcp_f32_e32 v1, v1
	v_rcp_f32_e32 v169, v169
	v_rcp_f32_e32 v184, v184
	v_rcp_f32_e32 v185, v185
	v_rcp_f32_e32 v189, v182
	v_lshlrev_b64 v[174:175], 12, v[174:175]
	v_lshl_add_u64 v[174:175], s[26:27], 0, v[174:175]
	v_lshl_add_u64 v[174:175], v[174:175], 0, v[172:173]
	v_cvt_pk_bf16_f32 v182, v1, v169
	v_cvt_pk_bf16_f32 v183, v186, v187
	v_cvt_pk_bf16_f32 v184, v184, v185
	v_cvt_pk_bf16_f32 v185, v188, v189
	global_store_dwordx4 v[174:175], v[182:185], off nt
	s_nop 1
	v_pk_add_f32 v[182:183], v[104:105], v[136:137]
	v_pk_add_f32 v[184:185], v[102:103], v[134:135]
	v_mul_f32_e32 v182, 0xbfb8aa3b, v182
	v_exp_f32_e32 v182, v182
	v_mul_f32_e32 v1, 0xbfb8aa3b, v184
	v_mul_f32_e32 v169, 0xbfb8aa3b, v185
	v_pk_add_f32 v[184:185], v[98:99], v[130:131]
	v_add_f32_e32 v182, 1.0, v182
	v_rcp_f32_e32 v186, v182
; __device__ __forceinline__ u32x4 pack8(const f32x4 a, const f32x4 b) { u32x4 w; w.x = cvt_pk_bf16(a[0], a[1]); w.y = cvt_pk_bf16(a[2], a[3]); w.z = cvt_pk_bf16(b[0], b[1]); w.w = cvt_pk_bf16(b[2], b[3]); return w; }
; __device__ __forceinline__ f32x4 sigm4(const f32x4 v) { f32x4 o; o[0] = sigm(v[0]); o[1] = sigm(v[1]); o[2] = sigm(v[2]); o[3] = sigm(v[3]); return o; }
; #define EPI_ROWLOOP _Pragma("unroll") for (int ai = 0; ai < 2; ++ai) _Pragma("unroll") for (int m = 0; m < 4; ++m)
;     __device__ __forceinline__ void operator()(const f32x4 (&acc)[2][2][4][2], const Unit& u, int wr, int wc, int fr, int fq) const {
;     ...
;             EPI_ROWLOOP { bf16_t* rowp = GATES + (size_t)(row0 + ai * HALF + m * 16) * 2048 + gc;
; #pragma unroll
;                 for (int bj = 0; bj < 2; ++bj) *(u32x4*)(rowp + bj * HALF) = pack8(sigm4(acc[ai][bj][m][0] + bv[bj][0]), sigm4(acc[ai][bj][m][1] + bv[bj][1])); }
	v_mul_f32_e32 v182, 0xbfb8aa3b, v183
	v_exp_f32_e32 v182, v182
	v_mul_f32_e32 v184, 0xbfb8aa3b, v184
	v_mul_f32_e32 v185, 0xbfb8aa3b, v185
	v_exp_f32_e32 v1, v1
	v_add_f32_e32 v182, 1.0, v182
	v_rcp_f32_e32 v187, v182
	v_pk_add_f32 v[182:183], v[100:101], v[132:133]
	v_exp_f32_e32 v169, v169
	v_mul_f32_e32 v182, 0xbfb8aa3b, v182
	v_exp_f32_e32 v182, v182
	v_exp_f32_e32 v184, v184
	v_exp_f32_e32 v185, v185
	v_add_f32_e32 v1, 1.0, v1
	v_add_f32_e32 v182, 1.0, v182
	v_rcp_f32_e32 v188, v182
	v_mul_f32_e32 v182, 0xbfb8aa3b, v183
	v_exp_f32_e32 v182, v182
	v_add_f32_e32 v169, 1.0, v169
	v_add_f32_e32 v184, 1.0, v184
	v_add_f32_e32 v185, 1.0, v185
	v_add_f32_e32 v182, 1.0, v182
	v_rcp_f32_e32 v1, v1
	v_rcp_f32_e32 v169, v169
	v_rcp_f32_e32 v184, v184
	v_rcp_f32_e32 v185, v185
	v_rcp_f32_e32 v189, v182
	v_cvt_pk_bf16_f32 v182, v1, v169
	v_cvt_pk_bf16_f32 v183, v186, v187
	v_cvt_pk_bf16_f32 v184, v184, v185
	v_cvt_pk_bf16_f32 v185, v188, v189
	global_store_dwordx4 v[174:175], v[182:185], off offset:1024 nt
	v_or_b32_e32 v174, 32, v168
	v_ashrrev_i32_e32 v175, 31, v174
	v_pk_add_f32 v[182:183], v[96:97], v[144:145]
	v_pk_add_f32 v[184:185], v[94:95], v[142:143]
	v_mul_f32_e32 v182, 0xbfb8aa3b, v182
	v_exp_f32_e32 v182, v182
	v_mul_f32_e32 v1, 0xbfb8aa3b, v184
	v_mul_f32_e32 v169, 0xbfb8aa3b, v185
	v_pk_add_f32 v[184:185], v[90:91], v[138:139]
	v_add_f32_e32 v182, 1.0, v182
	v_rcp_f32_e32 v186, v182
	v_mul_f32_e32 v182, 0xbfb8aa3b, v183
	v_exp_f32_e32 v182, v182
	v_mul_f32_e32 v184, 0xbfb8aa3b, v184
	v_mul_f32_e32 v185, 0xbfb8aa3b, v185
	v_exp_f32_e32 v1, v1
	v_add_f32_e32 v182, 1.0, v182
	v_rcp_f32_e32 v187, v182
	v_pk_add_f32 v[182:183], v[92:93], v[140:141]
	v_exp_f32_e32 v169, v169
	v_mul_f32_e32 v182, 0xbfb8aa3b, v182
	v_exp_f32_e32 v182, v182
	v_exp_f32_e32 v184, v184
	v_exp_f32_e32 v185, v185
	v_add_f32_e32 v1, 1.0, v1
	v_add_f32_e32 v182, 1.0, v182
	v_rcp_f32_e32 v188, v182
	v_mul_f32_e32 v182, 0xbfb8aa3b, v183
	v_exp_f32_e32 v182, v182
	v_add_f32_e32 v169, 1.0, v169
	v_add_f32_e32 v184, 1.0, v184
	v_add_f32_e32 v185, 1.0, v185
	v_add_f32_e32 v182, 1.0, v182
	v_rcp_f32_e32 v1, v1
	v_rcp_f32_e32 v169, v169
	v_rcp_f32_e32 v184, v184
	v_rcp_f32_e32 v185, v185
	v_rcp_f32_e32 v189, v182
	v_lshlrev_b64 v[174:175], 12, v[174:175]
	v_lshl_add_u64 v[174:175], s[26:27], 0, v[174:175]
	v_lshl_add_u64 v[174:175], v[174:175], 0, v[172:173]
	v_cvt_pk_bf16_f32 v182, v1, v169
	v_cvt_pk_bf16_f32 v183, v186, v187
	v_cvt_pk_bf16_f32 v184, v184, v185
	v_cvt_pk_bf16_f32 v185, v188, v189
	global_store_dwordx4 v[174:175], v[182:185], off nt
	s_nop 1
	v_pk_add_f32 v[182:183], v[88:89], v[136:137]
	v_pk_add_f32 v[184:185], v[86:87], v[134:135]
	v_mul_f32_e32 v182, 0xbfb8aa3b, v182
	v_exp_f32_e32 v182, v182
	v_mul_f32_e32 v1, 0xbfb8aa3b, v184
	v_mul_f32_e32 v169, 0xbfb8aa3b, v185
	v_pk_add_f32 v[184:185], v[82:83], v[130:131]
	v_add_f32_e32 v182, 1.0, v182
	v_rcp_f32_e32 v186, v182
	v_mul_f32_e32 v182, 0xbfb8aa3b, v183
	v_exp_f32_e32 v182, v182
	v_mul_f32_e32 v184, 0xbfb8aa3b, v184
	v_mul_f32_e32 v185, 0xbfb8aa3b, v185
	v_exp_f32_e32 v1, v1
	v_add_f32_e32 v182, 1.0, v182
	v_rcp_f32_e32 v187, v182
	v_pk_add_f32 v[182:183], v[84:85], v[132:133]
	v_exp_f32_e32 v169, v169
	v_mul_f32_e32 v182, 0xbfb8aa3b, v182
	v_exp_f32_e32 v182, v182
	v_exp_f32_e32 v184, v184
	v_exp_f32_e32 v185, v185
	v_add_f32_e32 v1, 1.0, v1
	v_add_f32_e32 v182, 1.0, v182
	v_rcp_f32_e32 v188, v182
	v_mul_f32_e32 v182, 0xbfb8aa3b, v183
	v_exp_f32_e32 v182, v182
	v_add_f32_e32 v169, 1.0, v169
	v_add_f32_e32 v184, 1.0, v184
	v_add_f32_e32 v185, 1.0, v185
	v_add_f32_e32 v182, 1.0, v182
	v_rcp_f32_e32 v1, v1
	v_rcp_f32_e32 v169, v169
	v_rcp_f32_e32 v184, v184
	v_rcp_f32_e32 v185, v185
	v_rcp_f32_e32 v189, v182
	v_cvt_pk_bf16_f32 v182, v1, v169
	v_cvt_pk_bf16_f32 v183, v186, v187
	v_cvt_pk_bf16_f32 v184, v184, v185
	v_cvt_pk_bf16_f32 v185, v188, v189
	global_store_dwordx4 v[174:175], v[182:185], off offset:1024 nt
	v_or_b32_e32 v174, 48, v168
	v_ashrrev_i32_e32 v175, 31, v174
	v_lshlrev_b64 v[174:175], 12, v[174:175]
	v_lshl_add_u64 v[174:175], s[26:27], 0, v[174:175]
	v_lshl_add_u64 v[172:173], v[174:175], 0, v[172:173]
	v_pk_add_f32 v[174:175], v[80:81], v[144:145]
	v_pk_add_f32 v[182:183], v[78:79], v[142:143]
	v_mul_f32_e32 v174, 0xbfb8aa3b, v174
	v_exp_f32_e32 v174, v174
	v_mul_f32_e32 v1, 0xbfb8aa3b, v182
	v_mul_f32_e32 v169, 0xbfb8aa3b, v183
	v_pk_add_f32 v[182:183], v[74:75], v[138:139]
	v_add_f32_e32 v174, 1.0, v174
	v_rcp_f32_e32 v184, v174
	v_mul_f32_e32 v174, 0xbfb8aa3b, v175
	v_exp_f32_e32 v174, v174
	v_mul_f32_e32 v182, 0xbfb8aa3b, v182
	v_exp_f32_e32 v182, v182
	v_exp_f32_e32 v1, v1
	v_add_f32_e32 v174, 1.0, v174
	v_rcp_f32_e32 v185, v174
	v_pk_add_f32 v[174:175], v[76:77], v[140:141]
	v_add_f32_e32 v182, 1.0, v182
	v_mul_f32_e32 v174, 0xbfb8aa3b, v174
	v_mul_f32_e32 v175, 0xbfb8aa3b, v175
	v_exp_f32_e32 v174, v174
	v_exp_f32_e32 v175, v175
	v_rcp_f32_e32 v186, v182
	v_mul_f32_e32 v182, 0xbfb8aa3b, v183
	v_add_f32_e32 v174, 1.0, v174
	v_add_f32_e32 v175, 1.0, v175
	v_rcp_f32_e32 v174, v174
	v_rcp_f32_e32 v175, v175
	v_exp_f32_e32 v169, v169
	v_exp_f32_e32 v182, v182
	v_cvt_pk_bf16_f32 v183, v184, v185
	v_cvt_pk_bf16_f32 v185, v174, v175
	v_pk_add_f32 v[174:175], v[72:73], v[136:137]
	v_add_f32_e32 v1, 1.0, v1
	v_add_f32_e32 v169, 1.0, v169
	v_add_f32_e32 v182, 1.0, v182
	v_mul_f32_e32 v174, 0xbfb8aa3b, v174
	v_rcp_f32_e32 v1, v1
	v_rcp_f32_e32 v169, v169
	v_rcp_f32_e32 v187, v182
	v_exp_f32_e32 v174, v174
	v_cvt_pk_bf16_f32 v182, v1, v169
	v_cvt_pk_bf16_f32 v184, v186, v187
	v_add_f32_e32 v174, 1.0, v174
	global_store_dwordx4 v[172:173], v[182:185], off nt
	s_nop 1
	v_rcp_f32_e32 v184, v174
; __device__ __forceinline__ u32x4 pack8(const f32x4 a, const f32x4 b) { u32x4 w; w.x = cvt_pk_bf16(a[0], a[1]); w.y = cvt_pk_bf16(a[2], a[3]); w.z = cvt_pk_bf16(b[0], b[1]); w.w = cvt_pk_bf16(b[2], b[3]); return w; }
; __device__ __forceinline__ f32x4 sigm4(const f32x4 v) { f32x4 o; o[0] = sigm(v[0]); o[1] = sigm(v[1]); o[2] = sigm(v[2]); o[3] = sigm(v[3]); return o; }
; #define EPI_ROWLOOP _Pragma("unroll") for (int ai = 0; ai < 2; ++ai) _Pragma("unroll") for (int m = 0; m < 4; ++m)
;     __device__ __forceinline__ void operator()(const f32x4 (&acc)[2][2][4][2], const Unit& u, int wr, int wc, int fr, int fq) const {
;     ...
;             EPI_ROWLOOP { bf16_t* rowp = GATES + (size_t)(row0 + ai * HALF + m * 16) * 2048 + gc;
; #pragma unroll
;                 for (int bj = 0; bj < 2; ++bj) *(u32x4*)(rowp + bj * HALF) = pack8(sigm4(acc[ai][bj][m][0] + bv[bj][0]), sigm4(acc[ai][bj][m][1] + bv[bj][1])); }
	v_mul_f32_e32 v174, 0xbfb8aa3b, v175
	v_exp_f32_e32 v174, v174
	v_pk_add_f32 v[182:183], v[70:71], v[134:135]
	v_add_f32_e32 v174, 1.0, v174
	v_mul_f32_e32 v1, 0xbfb8aa3b, v182
	v_mul_f32_e32 v169, 0xbfb8aa3b, v183
	v_rcp_f32_e32 v185, v174
	v_pk_add_f32 v[174:175], v[68:69], v[132:133]
	v_pk_add_f32 v[182:183], v[66:67], v[130:131]
	v_mul_f32_e32 v174, 0xbfb8aa3b, v174
	v_mul_f32_e32 v182, 0xbfb8aa3b, v182
	v_mul_f32_e32 v175, 0xbfb8aa3b, v175
	v_exp_f32_e32 v182, v182
	v_exp_f32_e32 v174, v174
	v_exp_f32_e32 v175, v175
	v_exp_f32_e32 v1, v1
	v_add_f32_e32 v182, 1.0, v182
	v_add_f32_e32 v174, 1.0, v174
	v_add_f32_e32 v175, 1.0, v175
	v_rcp_f32_e32 v186, v182
	v_mul_f32_e32 v182, 0xbfb8aa3b, v183
	v_rcp_f32_e32 v174, v174
	v_rcp_f32_e32 v175, v175
	v_exp_f32_e32 v169, v169
	v_exp_f32_e32 v182, v182
	v_cvt_pk_bf16_f32 v183, v184, v185
	v_cvt_pk_bf16_f32 v185, v174, v175
	v_pk_add_f32 v[174:175], v[64:65], v[144:145]
	v_add_f32_e32 v1, 1.0, v1
	v_add_f32_e32 v169, 1.0, v169
	v_add_f32_e32 v182, 1.0, v182
	v_mul_f32_e32 v174, 0xbfb8aa3b, v174
	v_rcp_f32_e32 v1, v1
	v_rcp_f32_e32 v169, v169
	v_rcp_f32_e32 v187, v182
	v_exp_f32_e32 v174, v174
	v_cvt_pk_bf16_f32 v182, v1, v169
	v_cvt_pk_bf16_f32 v184, v186, v187
	v_add_f32_e32 v174, 1.0, v174
	global_store_dwordx4 v[172:173], v[182:185], off offset:1024 nt
	v_lshl_add_u64 v[172:173], v[170:171], 0, s[0:1]
	s_mov_b32 s0, 0x80000
	v_pk_add_f32 v[182:183], v[62:63], v[142:143]
	v_rcp_f32_e32 v184, v174
	v_mul_f32_e32 v174, 0xbfb8aa3b, v175
	v_mul_f32_e32 v1, 0xbfb8aa3b, v182
	v_mul_f32_e32 v169, 0xbfb8aa3b, v183
	v_exp_f32_e32 v174, v174
	v_pk_add_f32 v[182:183], v[58:59], v[138:139]
	v_exp_f32_e32 v1, v1
	v_mul_f32_e32 v182, 0xbfb8aa3b, v182
	v_exp_f32_e32 v182, v182
	v_add_f32_e32 v174, 1.0, v174
	v_rcp_f32_e32 v185, v174
	v_pk_add_f32 v[174:175], v[60:61], v[140:141]
	v_add_f32_e32 v182, 1.0, v182
	v_mul_f32_e32 v174, 0xbfb8aa3b, v174
	v_mul_f32_e32 v175, 0xbfb8aa3b, v175
	v_rcp_f32_e32 v186, v182
	v_mul_f32_e32 v182, 0xbfb8aa3b, v183
	v_exp_f32_e32 v174, v174
	v_exp_f32_e32 v175, v175
	v_exp_f32_e32 v169, v169
	v_exp_f32_e32 v182, v182
	v_add_f32_e32 v174, 1.0, v174
	v_add_f32_e32 v175, 1.0, v175
	v_add_f32_e32 v1, 1.0, v1
	v_add_f32_e32 v169, 1.0, v169
	v_add_f32_e32 v182, 1.0, v182
	v_rcp_f32_e32 v174, v174
	v_rcp_f32_e32 v175, v175
	v_rcp_f32_e32 v1, v1
	v_rcp_f32_e32 v169, v169
	v_rcp_f32_e32 v187, v182
	v_cvt_pk_bf16_f32 v183, v184, v185
	v_cvt_pk_bf16_f32 v185, v174, v175
	v_add_co_u32_e32 v174, vcc, s0, v170
	v_cvt_pk_bf16_f32 v182, v1, v169
	v_cvt_pk_bf16_f32 v184, v186, v187
	v_addc_co_u32_e32 v175, vcc, 0, v171, vcc
	global_store_dwordx4 v[174:175], v[182:185], off nt
	v_pk_add_f32 v[174:175], v[56:57], v[136:137]
	s_mov_b64 s[0:1], 0x90000
	v_mul_f32_e32 v174, 0xbfb8aa3b, v174
	v_exp_f32_e32 v174, v174
	v_pk_add_f32 v[182:183], v[54:55], v[134:135]
	v_add_f32_e32 v174, 1.0, v174
	v_rcp_f32_e32 v184, v174
	v_mul_f32_e32 v174, 0xbfb8aa3b, v175
	v_exp_f32_e32 v174, v174
	v_mul_f32_e32 v1, 0xbfb8aa3b, v182
	v_mul_f32_e32 v169, 0xbfb8aa3b, v183
	v_pk_add_f32 v[182:183], v[50:51], v[130:131]
	v_add_f32_e32 v174, 1.0, v174
	v_rcp_f32_e32 v185, v174
	v_pk_add_f32 v[174:175], v[52:53], v[132:133]
	v_mul_f32_e32 v182, 0xbfb8aa3b, v182
	v_mul_f32_e32 v174, 0xbfb8aa3b, v174
	v_mul_f32_e32 v175, 0xbfb8aa3b, v175
	v_exp_f32_e32 v182, v182
	v_exp_f32_e32 v174, v174
	v_exp_f32_e32 v175, v175
	v_exp_f32_e32 v1, v1
	v_add_f32_e32 v182, 1.0, v182
	v_add_f32_e32 v174, 1.0, v174
	v_add_f32_e32 v175, 1.0, v175
	v_rcp_f32_e32 v186, v182
	v_mul_f32_e32 v182, 0xbfb8aa3b, v183
	v_rcp_f32_e32 v174, v174
	v_rcp_f32_e32 v175, v175
	v_exp_f32_e32 v169, v169
	v_exp_f32_e32 v182, v182
	v_cvt_pk_bf16_f32 v183, v184, v185
	v_cvt_pk_bf16_f32 v185, v174, v175
	v_pk_add_f32 v[174:175], v[48:49], v[144:145]
	v_add_f32_e32 v1, 1.0, v1
	v_add_f32_e32 v169, 1.0, v169
	v_add_f32_e32 v182, 1.0, v182
	v_mul_f32_e32 v174, 0xbfb8aa3b, v174
	v_rcp_f32_e32 v1, v1
	v_rcp_f32_e32 v169, v169
	v_rcp_f32_e32 v187, v182
	v_exp_f32_e32 v174, v174
	v_cvt_pk_bf16_f32 v182, v1, v169
	v_cvt_pk_bf16_f32 v184, v186, v187
	v_add_f32_e32 v174, 1.0, v174
	global_store_dwordx4 v[172:173], v[182:185], off offset:1024 nt
	v_lshl_add_u64 v[172:173], v[170:171], 0, s[0:1]
	s_mov_b32 s0, 0x90000
	v_pk_add_f32 v[182:183], v[46:47], v[142:143]
	v_rcp_f32_e32 v184, v174
	v_mul_f32_e32 v174, 0xbfb8aa3b, v175
	v_mul_f32_e32 v1, 0xbfb8aa3b, v182
	v_mul_f32_e32 v169, 0xbfb8aa3b, v183
	v_exp_f32_e32 v174, v174
	v_pk_add_f32 v[182:183], v[42:43], v[138:139]
	v_exp_f32_e32 v1, v1
	v_mul_f32_e32 v182, 0xbfb8aa3b, v182
	v_exp_f32_e32 v182, v182
	v_add_f32_e32 v174, 1.0, v174
	v_rcp_f32_e32 v185, v174
	v_pk_add_f32 v[174:175], v[44:45], v[140:141]
	v_add_f32_e32 v182, 1.0, v182
	v_mul_f32_e32 v174, 0xbfb8aa3b, v174
	v_mul_f32_e32 v175, 0xbfb8aa3b, v175
	v_rcp_f32_e32 v186, v182
	v_mul_f32_e32 v182, 0xbfb8aa3b, v183
	v_exp_f32_e32 v174, v174
	v_exp_f32_e32 v175, v175
	v_exp_f32_e32 v169, v169
	v_exp_f32_e32 v182, v182
	v_add_f32_e32 v174, 1.0, v174
	v_add_f32_e32 v175, 1.0, v175
	v_add_f32_e32 v1, 1.0, v1
	v_add_f32_e32 v169, 1.0, v169
	v_add_f32_e32 v182, 1.0, v182
	v_rcp_f32_e32 v174, v174
	v_rcp_f32_e32 v175, v175
	v_rcp_f32_e32 v1, v1
	v_rcp_f32_e32 v169, v169
	v_rcp_f32_e32 v187, v182
	v_cvt_pk_bf16_f32 v183, v184, v185
	v_cvt_pk_bf16_f32 v185, v174, v175
	v_add_co_u32_e32 v174, vcc, s0, v170
	v_cvt_pk_bf16_f32 v182, v1, v169
	v_cvt_pk_bf16_f32 v184, v186, v187
	v_addc_co_u32_e32 v175, vcc, 0, v171, vcc
	global_store_dwordx4 v[174:175], v[182:185], off nt
	v_pk_add_f32 v[174:175], v[40:41], v[136:137]
	s_mov_b64 s[0:1], 0xa0000
	v_mul_f32_e32 v174, 0xbfb8aa3b, v174
; __device__ __forceinline__ u32x4 pack8(const f32x4 a, const f32x4 b) { u32x4 w; w.x = cvt_pk_bf16(a[0], a[1]); w.y = cvt_pk_bf16(a[2], a[3]); w.z = cvt_pk_bf16(b[0], b[1]); w.w = cvt_pk_bf16(b[2], b[3]); return w; }
; __device__ __forceinline__ f32x4 sigm4(const f32x4 v) { f32x4 o; o[0] = sigm(v[0]); o[1] = sigm(v[1]); o[2] = sigm(v[2]); o[3] = sigm(v[3]); return o; }
; #define EPI_ROWLOOP _Pragma("unroll") for (int ai = 0; ai < 2; ++ai) _Pragma("unroll") for (int m = 0; m < 4; ++m)
;     __device__ __forceinline__ void operator()(const f32x4 (&acc)[2][2][4][2], const Unit& u, int wr, int wc, int fr, int fq) const {
;     ...
;             EPI_ROWLOOP { bf16_t* rowp = GATES + (size_t)(row0 + ai * HALF + m * 16) * 2048 + gc;
; #pragma unroll
;                 for (int bj = 0; bj < 2; ++bj) *(u32x4*)(rowp + bj * HALF) = pack8(sigm4(acc[ai][bj][m][0] + bv[bj][0]), sigm4(acc[ai][bj][m][1] + bv[bj][1])); }
	v_exp_f32_e32 v174, v174
	v_pk_add_f32 v[182:183], v[38:39], v[134:135]
	v_add_f32_e32 v174, 1.0, v174
	v_rcp_f32_e32 v184, v174
	v_mul_f32_e32 v174, 0xbfb8aa3b, v175
	v_exp_f32_e32 v174, v174
	v_mul_f32_e32 v1, 0xbfb8aa3b, v182
	v_mul_f32_e32 v169, 0xbfb8aa3b, v183
	v_pk_add_f32 v[182:183], v[34:35], v[130:131]
	v_add_f32_e32 v174, 1.0, v174
	v_rcp_f32_e32 v185, v174
	v_pk_add_f32 v[174:175], v[36:37], v[132:133]
	v_mul_f32_e32 v182, 0xbfb8aa3b, v182
	v_mul_f32_e32 v174, 0xbfb8aa3b, v174
	v_mul_f32_e32 v175, 0xbfb8aa3b, v175
	v_exp_f32_e32 v182, v182
	v_exp_f32_e32 v174, v174
	v_exp_f32_e32 v175, v175
	v_exp_f32_e32 v1, v1
	v_add_f32_e32 v182, 1.0, v182
	v_add_f32_e32 v174, 1.0, v174
	v_add_f32_e32 v175, 1.0, v175
	v_rcp_f32_e32 v186, v182
	v_mul_f32_e32 v182, 0xbfb8aa3b, v183
	v_rcp_f32_e32 v174, v174
	v_rcp_f32_e32 v175, v175
	v_exp_f32_e32 v169, v169
	v_exp_f32_e32 v182, v182
	v_cvt_pk_bf16_f32 v183, v184, v185
	v_cvt_pk_bf16_f32 v185, v174, v175
	v_pk_add_f32 v[174:175], v[32:33], v[144:145]
	v_add_f32_e32 v1, 1.0, v1
	v_add_f32_e32 v169, 1.0, v169
	v_add_f32_e32 v182, 1.0, v182
	v_mul_f32_e32 v174, 0xbfb8aa3b, v174
	v_rcp_f32_e32 v1, v1
	v_rcp_f32_e32 v169, v169
	v_rcp_f32_e32 v187, v182
	v_exp_f32_e32 v174, v174
	v_pk_add_f32 v[144:145], v[16:17], v[144:145]
	v_cvt_pk_bf16_f32 v182, v1, v169
	v_cvt_pk_bf16_f32 v184, v186, v187
	v_add_f32_e32 v174, 1.0, v174
	global_store_dwordx4 v[172:173], v[182:185], off offset:1024 nt
	v_lshl_add_u64 v[172:173], v[170:171], 0, s[0:1]
	s_mov_b32 s0, 0xa0000
	v_pk_add_f32 v[182:183], v[30:31], v[142:143]
	v_rcp_f32_e32 v184, v174
	v_mul_f32_e32 v174, 0xbfb8aa3b, v175
	v_mul_f32_e32 v1, 0xbfb8aa3b, v182
	v_mul_f32_e32 v169, 0xbfb8aa3b, v183
	v_exp_f32_e32 v174, v174
	v_pk_add_f32 v[182:183], v[26:27], v[138:139]
	v_exp_f32_e32 v1, v1
	v_mul_f32_e32 v182, 0xbfb8aa3b, v182
	v_exp_f32_e32 v182, v182
	v_add_f32_e32 v174, 1.0, v174
	v_rcp_f32_e32 v185, v174
	v_pk_add_f32 v[174:175], v[28:29], v[140:141]
	v_add_f32_e32 v182, 1.0, v182
	v_mul_f32_e32 v174, 0xbfb8aa3b, v174
	v_mul_f32_e32 v175, 0xbfb8aa3b, v175
	v_rcp_f32_e32 v186, v182
	v_mul_f32_e32 v182, 0xbfb8aa3b, v183
	v_exp_f32_e32 v174, v174
	v_exp_f32_e32 v175, v175
	v_exp_f32_e32 v169, v169
	v_exp_f32_e32 v182, v182
	v_add_f32_e32 v174, 1.0, v174
	v_add_f32_e32 v175, 1.0, v175
	v_add_f32_e32 v1, 1.0, v1
	v_add_f32_e32 v169, 1.0, v169
	v_add_f32_e32 v182, 1.0, v182
	v_rcp_f32_e32 v174, v174
	v_rcp_f32_e32 v175, v175
	v_rcp_f32_e32 v1, v1
	v_rcp_f32_e32 v169, v169
	v_rcp_f32_e32 v187, v182
	v_cvt_pk_bf16_f32 v183, v184, v185
	v_cvt_pk_bf16_f32 v185, v174, v175
	v_add_co_u32_e32 v174, vcc, s0, v170
	v_cvt_pk_bf16_f32 v182, v1, v169
	v_cvt_pk_bf16_f32 v184, v186, v187
	v_addc_co_u32_e32 v175, vcc, 0, v171, vcc
	global_store_dwordx4 v[174:175], v[182:185], off nt
	v_pk_add_f32 v[174:175], v[24:25], v[136:137]
	v_pk_add_f32 v[138:139], v[10:11], v[138:139]
	v_pk_add_f32 v[182:183], v[22:23], v[134:135]
	v_mul_f32_e32 v174, 0xbfb8aa3b, v174
	v_mul_f32_e32 v1, 0xbfb8aa3b, v182
	v_mul_f32_e32 v169, 0xbfb8aa3b, v183
	v_pk_add_f32 v[182:183], v[18:19], v[130:131]
	v_exp_f32_e32 v174, v174
	v_mul_f32_e32 v182, 0xbfb8aa3b, v182
	v_exp_f32_e32 v182, v182
	v_exp_f32_e32 v1, v1
	v_exp_f32_e32 v169, v169
	v_add_f32_e32 v174, 1.0, v174
	v_add_f32_e32 v182, 1.0, v182
	v_rcp_f32_e32 v186, v182
	v_mul_f32_e32 v182, 0xbfb8aa3b, v183
	v_mul_f32_e32 v138, 0xbfb8aa3b, v138
	v_add_f32_e32 v1, 1.0, v1
	v_add_f32_e32 v169, 1.0, v169
	v_rcp_f32_e32 v184, v174
	v_mul_f32_e32 v174, 0xbfb8aa3b, v175
	v_exp_f32_e32 v182, v182
	v_exp_f32_e32 v138, v138
	v_rcp_f32_e32 v1, v1
	v_rcp_f32_e32 v169, v169
	v_exp_f32_e32 v174, v174
	v_add_f32_e32 v182, 1.0, v182
	v_pk_add_f32 v[142:143], v[14:15], v[142:143]
	v_add_f32_e32 v138, 1.0, v138
	v_add_f32_e32 v174, 1.0, v174
	v_rcp_f32_e32 v187, v182
	v_cvt_pk_bf16_f32 v182, v1, v169
	v_mul_f32_e32 v1, 0xbfb8aa3b, v142
	v_mul_f32_e32 v142, 0xbfb8aa3b, v143
	v_mul_f32_e32 v143, 0xbfb8aa3b, v144
	v_mul_f32_e32 v144, 0xbfb8aa3b, v145
	v_rcp_f32_e32 v145, v138
	v_mul_f32_e32 v138, 0xbfb8aa3b, v139
	v_rcp_f32_e32 v185, v174
	v_pk_add_f32 v[174:175], v[20:21], v[132:133]
	v_exp_f32_e32 v138, v138
	v_mul_f32_e32 v174, 0xbfb8aa3b, v174
	v_mul_f32_e32 v175, 0xbfb8aa3b, v175
	v_exp_f32_e32 v174, v174
	v_exp_f32_e32 v175, v175
	v_pk_add_f32 v[140:141], v[12:13], v[140:141]
	v_add_f32_e32 v138, 1.0, v138
	v_rcp_f32_e32 v169, v138
	v_mul_f32_e32 v138, 0xbfb8aa3b, v140
	v_add_f32_e32 v174, 1.0, v174
	v_add_f32_e32 v175, 1.0, v175
	v_exp_f32_e32 v138, v138
	v_rcp_f32_e32 v174, v174
	v_rcp_f32_e32 v175, v175
	v_exp_f32_e32 v1, v1
	v_exp_f32_e32 v142, v142
	v_add_f32_e32 v138, 1.0, v138
	v_pk_add_f32 v[130:131], v[2:3], v[130:131]
	v_cvt_pk_bf16_f32 v183, v184, v185
	v_cvt_pk_bf16_f32 v185, v174, v175
	v_rcp_f32_e32 v174, v138
	v_mul_f32_e32 v138, 0xbfb8aa3b, v141
	v_mul_f32_e32 v130, 0xbfb8aa3b, v130
	v_add_f32_e32 v1, 1.0, v1
	v_add_f32_e32 v142, 1.0, v142
	v_exp_f32_e32 v138, v138
	v_exp_f32_e32 v130, v130
	v_rcp_f32_e32 v1, v1
	v_rcp_f32_e32 v142, v142
	v_exp_f32_e32 v143, v143
	v_exp_f32_e32 v144, v144
	v_add_f32_e32 v138, 1.0, v138
	v_pk_add_f32 v[136:137], v[8:9], v[136:137]
	v_pk_add_f32 v[134:135], v[6:7], v[134:135]
	v_add_f32_e32 v130, 1.0, v130
	v_add_f32_e32 v143, 1.0, v143
	v_add_f32_e32 v144, 1.0, v144
	v_rcp_f32_e32 v141, v138
	v_cvt_pk_bf16_f32 v138, v1, v142
	v_mul_f32_e32 v1, 0xbfb8aa3b, v134
	v_mul_f32_e32 v134, 0xbfb8aa3b, v135
	v_mul_f32_e32 v135, 0xbfb8aa3b, v136
	v_mul_f32_e32 v136, 0xbfb8aa3b, v137
	v_rcp_f32_e32 v137, v130
	v_mul_f32_e32 v130, 0xbfb8aa3b, v131
	v_rcp_f32_e32 v143, v143
	v_rcp_f32_e32 v144, v144
	v_exp_f32_e32 v130, v130
	v_cvt_pk_bf16_f32 v184, v186, v187
	s_mov_b64 s[0:1], 0xb0000
	global_store_dwordx4 v[172:173], v[182:185], off offset:1024 nt
	v_lshl_add_u64 v[172:173], v[170:171], 0, s[0:1]
	s_mov_b32 s0, 0xb0000
	v_add_co_u32_e32 v142, vcc, s0, v170
	v_cvt_pk_bf16_f32 v139, v143, v144
	v_cvt_pk_bf16_f32 v140, v145, v169
	v_cvt_pk_bf16_f32 v141, v174, v141
	v_addc_co_u32_e32 v143, vcc, 0, v171, vcc
	v_pk_add_f32 v[132:133], v[4:5], v[132:133]
	v_add_f32_e32 v130, 1.0, v130
	global_store_dwordx4 v[142:143], v[138:141], off nt
	v_exp_f32_e32 v1, v1
	v_exp_f32_e32 v134, v134
	v_rcp_f32_e32 v138, v130
	v_mul_f32_e32 v130, 0xbfb8aa3b, v132
	v_exp_f32_e32 v130, v130
	v_exp_f32_e32 v135, v135
	v_exp_f32_e32 v136, v136
	v_add_f32_e32 v1, 1.0, v1
	v_add_f32_e32 v130, 1.0, v130
	v_rcp_f32_e32 v139, v130
	v_mul_f32_e32 v130, 0xbfb8aa3b, v133
	v_exp_f32_e32 v130, v130
	v_add_f32_e32 v134, 1.0, v134
	v_add_f32_e32 v135, 1.0, v135
	v_add_f32_e32 v136, 1.0, v136
	v_add_f32_e32 v130, 1.0, v130
	v_rcp_f32_e32 v1, v1
	v_rcp_f32_e32 v134, v134
	v_rcp_f32_e32 v135, v135
	v_rcp_f32_e32 v136, v136
	v_rcp_f32_e32 v133, v130
	v_cvt_pk_bf16_f32 v130, v1, v134
	v_cvt_pk_bf16_f32 v132, v137, v138
	v_cvt_pk_bf16_f32 v131, v135, v136
	v_cvt_pk_bf16_f32 v133, v139, v133
	global_store_dwordx4 v[172:173], v[130:133], off offset:1024 nt

; __device__ __forceinline__ u32x4 pack8(const f32x4 a, const f32x4 b) { u32x4 w; w.x = cvt_pk_bf16(a[0], a[1]); w.y = cvt_pk_bf16(a[2], a[3]); w.z = cvt_pk_bf16(b[0], b[1]); w.w = cvt_pk_bf16(b[2], b[3]); return w; }
; #define EPI_ROWLOOP _Pragma("unroll") for (int ai = 0; ai < 2; ++ai) _Pragma("unroll") for (int m = 0; m < 4; ++m)
;     __device__ __forceinline__ void operator()(const f32x4 (&acc)[2][2][4][2], const Unit& u, int wr, int wc, int fr, int fq) const {
;     ...
;         EPI_ROWLOOP { const int r = row0 + ai * HALF + m * 16;
; #pragma unroll
;             for (int bj = 0; bj < 2; ++bj) { const int c = c0 + bj * HALF; f32x4 g0, g1; unpack8(*(const u32x4*)(GATES + (size_t)r * 2048 + (u.sel ? 1024 : 0) + c), g0, g1);
;                 f32x4 v0 = acc[ai][bj][m][0] * g0, v1 = acc[ai][bj][m][1] * g1;
;                 if (u.sel) { f32x4 t0, t1; unpack8(*(const u32x4*)(T + (size_t)r * 1024 + c), t0, t1); v0 += t0; v1 += t1; *(u32x4*)(MIX + (size_t)r * 1024 + c) = pack8(v0, v1); }
;                 else *(u32x4*)(T + (size_t)r * 1024 + c) = pack8(v0, v1); } }
.LBB0_731:
	v_lshl_add_u32 v162, s14, 8, v166
	v_lshl_or_b32 v163, s77, 8, v168
	s_cmp_eq_u32 s78, 0
	s_cselect_b32 s14, 0, 0x8000
	v_and_b32_e32 v200, 15, v162
	v_and_b32_e32 v160, -16, v162
	v_lshlrev_b32_e32 v160, 12, v160
	v_lshl_or_b32 v160, v200, 6, v160
	v_lshrrev_b32_e32 v200, 8, v163
	v_lshl_add_u32 v160, v200, 13, v160
	v_bfe_u32 v200, v163, 5, 2
	v_lshl_add_u32 v160, v200, 11, v160
	v_and_b32_e32 v200, 31, v163
	v_lshl_add_u32 v160, v200, 1, v160
	v_add_u32_e32 v160, s14, v160
	v_mov_b32_e32 v161, 0
	v_lshlrev_b32_e32 v164, 11, v162
	v_lshl_add_u32 v164, v163, 1, v164
	v_mov_b32_e32 v165, 0
	v_lshl_add_u64 v[160:161], s[26:27], 0, v[160:161]
	s_mov_b64 s[6:7], 0x10000
	s_mov_b64 s[52:53], 0x50000
	global_load_dwordx4 v[172:175], v[160:161], off
	global_load_dwordx4 v[176:179], v[160:161], off offset:1024
	v_lshl_add_u64 v[160:161], v[160:161], 0, s[6:7]
	global_load_dwordx4 v[180:183], v[160:161], off
	global_load_dwordx4 v[184:187], v[160:161], off offset:1024
	v_lshl_add_u64 v[160:161], v[160:161], 0, s[6:7]
	global_load_dwordx4 v[188:191], v[160:161], off
	global_load_dwordx4 v[192:195], v[160:161], off offset:1024
	v_lshl_add_u64 v[160:161], v[160:161], 0, s[6:7]
	global_load_dwordx4 v[196:199], v[160:161], off
	global_load_dwordx4 v[202:205], v[160:161], off offset:1024
	v_lshl_add_u64 v[160:161], v[160:161], 0, s[52:53]
	global_load_dwordx4 v[206:209], v[160:161], off
	global_load_dwordx4 v[210:213], v[160:161], off offset:1024
	v_lshl_add_u64 v[160:161], v[160:161], 0, s[6:7]
	global_load_dwordx4 v[214:217], v[160:161], off
	global_load_dwordx4 v[218:221], v[160:161], off offset:1024
	v_lshl_add_u64 v[160:161], v[160:161], 0, s[6:7]
	global_load_dwordx4 v[222:225], v[160:161], off
	global_load_dwordx4 v[226:229], v[160:161], off offset:1024
	v_lshl_add_u64 v[160:161], v[160:161], 0, s[6:7]
	global_load_dwordx4 v[230:233], v[160:161], off
	global_load_dwordx4 v[236:239], v[160:161], off offset:1024
	s_cmp_eq_u32 s78, 0
	s_cbranch_scc1 .Lp5_sel0
	v_lshl_add_u64 v[160:161], s[34:35], 0, v[164:165]
	v_lshl_add_u64 v[164:165], s[24:25], 0, v[164:165]
	s_mov_b64 s[6:7], 0x8000
	s_mov_b64 s[52:53], 0x28000
	global_load_dwordx4 v[240:243], v[160:161], off
	global_load_dwordx4 v[244:247], v[160:161], off offset:256
	v_lshl_add_u64 v[160:161], v[160:161], 0, s[6:7]
	global_load_dwordx4 v[248:251], v[160:161], off
	global_load_dwordx4 v[128:131], v[160:161], off offset:256
	v_lshl_add_u64 v[160:161], v[160:161], 0, s[6:7]
	global_load_dwordx4 v[148:151], v[160:161], off
	s_waitcnt vmcnt(4)
	v_lshlrev_b32_e32 v152, 16, v172
	v_and_b32_e32 v153, 0xffff0000, v172
	v_pk_mul_f32 v[120:121], v[120:121], v[152:153]
	v_lshlrev_b32_e32 v154, 16, v173
	v_and_b32_e32 v155, 0xffff0000, v173
	v_pk_mul_f32 v[122:123], v[122:123], v[154:155]
	v_lshlrev_b32_e32 v156, 16, v174
	v_and_b32_e32 v157, 0xffff0000, v174
	v_pk_mul_f32 v[124:125], v[124:125], v[156:157]
	v_lshlrev_b32_e32 v158, 16, v175
	v_and_b32_e32 v159, 0xffff0000, v175
	v_pk_mul_f32 v[126:127], v[126:127], v[158:159]
	v_lshlrev_b32_e32 v152, 16, v240
	v_and_b32_e32 v153, 0xffff0000, v240
	v_pk_add_f32 v[120:121], v[120:121], v[152:153]
	v_lshlrev_b32_e32 v154, 16, v241
	v_and_b32_e32 v155, 0xffff0000, v241
	v_pk_add_f32 v[122:123], v[122:123], v[154:155]
	v_lshlrev_b32_e32 v156, 16, v242
	v_and_b32_e32 v157, 0xffff0000, v242
	v_pk_add_f32 v[124:125], v[124:125], v[156:157]
	v_lshlrev_b32_e32 v158, 16, v243
	v_and_b32_e32 v159, 0xffff0000, v243
	v_pk_add_f32 v[126:127], v[126:127], v[158:159]
	v_cvt_pk_bf16_f32 v120, v120, v121
	v_cvt_pk_bf16_f32 v121, v122, v123
	v_cvt_pk_bf16_f32 v122, v124, v125
	v_cvt_pk_bf16_f32 v123, v126, v127
	global_load_dwordx4 v[172:175], v[160:161], off offset:256
	v_lshl_add_u64 v[160:161], v[160:161], 0, s[6:7]
	s_waitcnt vmcnt(4)
	v_lshlrev_b32_e32 v152, 16, v176
	v_and_b32_e32 v153, 0xffff0000, v176
	v_pk_mul_f32 v[116:117], v[116:117], v[152:153]
	v_lshlrev_b32_e32 v154, 16, v177
	v_and_b32_e32 v155, 0xffff0000, v177
	v_pk_mul_f32 v[118:119], v[118:119], v[154:155]
	v_lshlrev_b32_e32 v156, 16, v178
	v_and_b32_e32 v157, 0xffff0000, v178
	v_pk_mul_f32 v[112:113], v[112:113], v[156:157]
	v_lshlrev_b32_e32 v158, 16, v179
	v_and_b32_e32 v159, 0xffff0000, v179
	v_pk_mul_f32 v[114:115], v[114:115], v[158:159]
	v_lshlrev_b32_e32 v152, 16, v244
	v_and_b32_e32 v153, 0xffff0000, v244
	v_pk_add_f32 v[116:117], v[116:117], v[152:153]
	v_lshlrev_b32_e32 v154, 16, v245
	v_and_b32_e32 v155, 0xffff0000, v245
	v_pk_add_f32 v[118:119], v[118:119], v[154:155]
	v_lshlrev_b32_e32 v156, 16, v246
	v_and_b32_e32 v157, 0xffff0000, v246
	v_pk_add_f32 v[112:113], v[112:113], v[156:157]
	v_lshlrev_b32_e32 v158, 16, v247
	v_and_b32_e32 v159, 0xffff0000, v247
	v_pk_add_f32 v[114:115], v[114:115], v[158:159]
	v_cvt_pk_bf16_f32 v116, v116, v117
	v_cvt_pk_bf16_f32 v117, v118, v119
	v_cvt_pk_bf16_f32 v118, v112, v113
	v_cvt_pk_bf16_f32 v119, v114, v115
	global_load_dwordx4 v[176:179], v[160:161], off
	s_waitcnt vmcnt(4)
	v_lshlrev_b32_e32 v152, 16, v180
	v_and_b32_e32 v153, 0xffff0000, v180
	v_pk_mul_f32 v[108:109], v[108:109], v[152:153]
	v_lshlrev_b32_e32 v154, 16, v181
	v_and_b32_e32 v155, 0xffff0000, v181
	v_pk_mul_f32 v[110:111], v[110:111], v[154:155]
	v_lshlrev_b32_e32 v156, 16, v182
	v_and_b32_e32 v157, 0xffff0000, v182
	v_pk_mul_f32 v[104:105], v[104:105], v[156:157]
	v_lshlrev_b32_e32 v158, 16, v183
	v_and_b32_e32 v159, 0xffff0000, v183
	v_pk_mul_f32 v[106:107], v[106:107], v[158:159]
	v_lshlrev_b32_e32 v152, 16, v248
	v_and_b32_e32 v153, 0xffff0000, v248
	v_pk_add_f32 v[108:109], v[108:109], v[152:153]
	v_lshlrev_b32_e32 v154, 16, v249
	v_and_b32_e32 v155, 0xffff0000, v249
	v_pk_add_f32 v[110:111], v[110:111], v[154:155]
	v_lshlrev_b32_e32 v156, 16, v250
	v_and_b32_e32 v157, 0xffff0000, v250
	v_pk_add_f32 v[104:105], v[104:105], v[156:157]
	v_lshlrev_b32_e32 v158, 16, v251
	v_and_b32_e32 v159, 0xffff0000, v251
	v_pk_add_f32 v[106:107], v[106:107], v[158:159]
	v_cvt_pk_bf16_f32 v108, v108, v109
	v_cvt_pk_bf16_f32 v109, v110, v111
	v_cvt_pk_bf16_f32 v110, v104, v105
	v_cvt_pk_bf16_f32 v111, v106, v107
	global_load_dwordx4 v[180:183], v[160:161], off offset:256
	v_lshl_add_u64 v[160:161], v[160:161], 0, s[52:53]
	s_waitcnt vmcnt(4)
; __device__ __forceinline__ u32x4 pack8(const f32x4 a, const f32x4 b) { u32x4 w; w.x = cvt_pk_bf16(a[0], a[1]); w.y = cvt_pk_bf16(a[2], a[3]); w.z = cvt_pk_bf16(b[0], b[1]); w.w = cvt_pk_bf16(b[2], b[3]); return w; }
; #define EPI_ROWLOOP _Pragma("unroll") for (int ai = 0; ai < 2; ++ai) _Pragma("unroll") for (int m = 0; m < 4; ++m)
;     __device__ __forceinline__ void operator()(const f32x4 (&acc)[2][2][4][2], const Unit& u, int wr, int wc, int fr, int fq) const {
;     ...
;         EPI_ROWLOOP { const int r = row0 + ai * HALF + m * 16;
; #pragma unroll
;             for (int bj = 0; bj < 2; ++bj) { const int c = c0 + bj * HALF; f32x4 g0, g1; unpack8(*(const u32x4*)(GATES + (size_t)r * 2048 + (u.sel ? 1024 : 0) + c), g0, g1);
;                 f32x4 v0 = acc[ai][bj][m][0] * g0, v1 = acc[ai][bj][m][1] * g1;
;                 if (u.sel) { f32x4 t0, t1; unpack8(*(const u32x4*)(T + (size_t)r * 1024 + c), t0, t1); v0 += t0; v1 += t1; *(u32x4*)(MIX + (size_t)r * 1024 + c) = pack8(v0, v1); }
;                 else *(u32x4*)(T + (size_t)r * 1024 + c) = pack8(v0, v1); } }
	v_lshlrev_b32_e32 v152, 16, v184
	v_and_b32_e32 v153, 0xffff0000, v184
	v_pk_mul_f32 v[100:101], v[100:101], v[152:153]
	v_lshlrev_b32_e32 v154, 16, v185
	v_and_b32_e32 v155, 0xffff0000, v185
	v_pk_mul_f32 v[102:103], v[102:103], v[154:155]
	v_lshlrev_b32_e32 v156, 16, v186
	v_and_b32_e32 v157, 0xffff0000, v186
	v_pk_mul_f32 v[96:97], v[96:97], v[156:157]
	v_lshlrev_b32_e32 v158, 16, v187
	v_and_b32_e32 v159, 0xffff0000, v187
	v_pk_mul_f32 v[98:99], v[98:99], v[158:159]
	v_lshlrev_b32_e32 v152, 16, v128
	v_and_b32_e32 v153, 0xffff0000, v128
	v_pk_add_f32 v[100:101], v[100:101], v[152:153]
	v_lshlrev_b32_e32 v154, 16, v129
	v_and_b32_e32 v155, 0xffff0000, v129
	v_pk_add_f32 v[102:103], v[102:103], v[154:155]
	v_lshlrev_b32_e32 v156, 16, v130
	v_and_b32_e32 v157, 0xffff0000, v130
	v_pk_add_f32 v[96:97], v[96:97], v[156:157]
	v_lshlrev_b32_e32 v158, 16, v131
	v_and_b32_e32 v159, 0xffff0000, v131
	v_pk_add_f32 v[98:99], v[98:99], v[158:159]
	v_cvt_pk_bf16_f32 v100, v100, v101
	v_cvt_pk_bf16_f32 v101, v102, v103
	v_cvt_pk_bf16_f32 v102, v96, v97
	v_cvt_pk_bf16_f32 v103, v98, v99
	global_load_dwordx4 v[184:187], v[160:161], off
	s_waitcnt vmcnt(4)
	v_lshlrev_b32_e32 v152, 16, v188
	v_and_b32_e32 v153, 0xffff0000, v188
	v_pk_mul_f32 v[92:93], v[92:93], v[152:153]
	v_lshlrev_b32_e32 v154, 16, v189
	v_and_b32_e32 v155, 0xffff0000, v189
	v_pk_mul_f32 v[94:95], v[94:95], v[154:155]
	v_lshlrev_b32_e32 v156, 16, v190
	v_and_b32_e32 v157, 0xffff0000, v190
	v_pk_mul_f32 v[88:89], v[88:89], v[156:157]
	v_lshlrev_b32_e32 v158, 16, v191
	v_and_b32_e32 v159, 0xffff0000, v191
	v_pk_mul_f32 v[90:91], v[90:91], v[158:159]
	v_lshlrev_b32_e32 v152, 16, v148
	v_and_b32_e32 v153, 0xffff0000, v148
	v_pk_add_f32 v[92:93], v[92:93], v[152:153]
	v_lshlrev_b32_e32 v154, 16, v149
	v_and_b32_e32 v155, 0xffff0000, v149
	v_pk_add_f32 v[94:95], v[94:95], v[154:155]
	v_lshlrev_b32_e32 v156, 16, v150
	v_and_b32_e32 v157, 0xffff0000, v150
	v_pk_add_f32 v[88:89], v[88:89], v[156:157]
	v_lshlrev_b32_e32 v158, 16, v151
	v_and_b32_e32 v159, 0xffff0000, v151
	v_pk_add_f32 v[90:91], v[90:91], v[158:159]
	v_cvt_pk_bf16_f32 v92, v92, v93
	v_cvt_pk_bf16_f32 v93, v94, v95
	v_cvt_pk_bf16_f32 v94, v88, v89
	v_cvt_pk_bf16_f32 v95, v90, v91
	global_load_dwordx4 v[188:191], v[160:161], off offset:256
	v_lshl_add_u64 v[160:161], v[160:161], 0, s[6:7]
	s_waitcnt vmcnt(4)
	v_lshlrev_b32_e32 v152, 16, v192
	v_and_b32_e32 v153, 0xffff0000, v192
	v_pk_mul_f32 v[84:85], v[84:85], v[152:153]
	v_lshlrev_b32_e32 v154, 16, v193
	v_and_b32_e32 v155, 0xffff0000, v193
	v_pk_mul_f32 v[86:87], v[86:87], v[154:155]
	v_lshlrev_b32_e32 v156, 16, v194
	v_and_b32_e32 v157, 0xffff0000, v194
	v_pk_mul_f32 v[80:81], v[80:81], v[156:157]
	v_lshlrev_b32_e32 v158, 16, v195
	v_and_b32_e32 v159, 0xffff0000, v195
	v_pk_mul_f32 v[82:83], v[82:83], v[158:159]
	v_lshlrev_b32_e32 v152, 16, v172
	v_and_b32_e32 v153, 0xffff0000, v172
	v_pk_add_f32 v[84:85], v[84:85], v[152:153]
	v_lshlrev_b32_e32 v154, 16, v173
	v_and_b32_e32 v155, 0xffff0000, v173
	v_pk_add_f32 v[86:87], v[86:87], v[154:155]
	v_lshlrev_b32_e32 v156, 16, v174
	v_and_b32_e32 v157, 0xffff0000, v174
	v_pk_add_f32 v[80:81], v[80:81], v[156:157]
	v_lshlrev_b32_e32 v158, 16, v175
	v_and_b32_e32 v159, 0xffff0000, v175
	v_pk_add_f32 v[82:83], v[82:83], v[158:159]
	v_cvt_pk_bf16_f32 v84, v84, v85
	v_cvt_pk_bf16_f32 v85, v86, v87
	v_cvt_pk_bf16_f32 v86, v80, v81
	v_cvt_pk_bf16_f32 v87, v82, v83
	global_load_dwordx4 v[192:195], v[160:161], off
	s_waitcnt vmcnt(4)
	v_lshlrev_b32_e32 v152, 16, v196
	v_and_b32_e32 v153, 0xffff0000, v196
	v_pk_mul_f32 v[76:77], v[76:77], v[152:153]
	v_lshlrev_b32_e32 v154, 16, v197
	v_and_b32_e32 v155, 0xffff0000, v197
	v_pk_mul_f32 v[78:79], v[78:79], v[154:155]
	v_lshlrev_b32_e32 v156, 16, v198
	v_and_b32_e32 v157, 0xffff0000, v198
	v_pk_mul_f32 v[72:73], v[72:73], v[156:157]
	v_lshlrev_b32_e32 v158, 16, v199
	v_and_b32_e32 v159, 0xffff0000, v199
	v_pk_mul_f32 v[74:75], v[74:75], v[158:159]
	v_lshlrev_b32_e32 v152, 16, v176
	v_and_b32_e32 v153, 0xffff0000, v176
	v_pk_add_f32 v[76:77], v[76:77], v[152:153]
	v_lshlrev_b32_e32 v154, 16, v177
	v_and_b32_e32 v155, 0xffff0000, v177
	v_pk_add_f32 v[78:79], v[78:79], v[154:155]
	v_lshlrev_b32_e32 v156, 16, v178
	v_and_b32_e32 v157, 0xffff0000, v178
	v_pk_add_f32 v[72:73], v[72:73], v[156:157]
	v_lshlrev_b32_e32 v158, 16, v179
	v_and_b32_e32 v159, 0xffff0000, v179
	v_pk_add_f32 v[74:75], v[74:75], v[158:159]
	v_cvt_pk_bf16_f32 v76, v76, v77
	v_cvt_pk_bf16_f32 v77, v78, v79
	v_cvt_pk_bf16_f32 v78, v72, v73
	v_cvt_pk_bf16_f32 v79, v74, v75
	global_load_dwordx4 v[196:199], v[160:161], off offset:256
	v_lshl_add_u64 v[160:161], v[160:161], 0, s[6:7]
	s_waitcnt vmcnt(4)
	v_lshlrev_b32_e32 v152, 16, v202
	v_and_b32_e32 v153, 0xffff0000, v202
	v_pk_mul_f32 v[68:69], v[68:69], v[152:153]
	v_lshlrev_b32_e32 v154, 16, v203
	v_and_b32_e32 v155, 0xffff0000, v203
	v_pk_mul_f32 v[70:71], v[70:71], v[154:155]
	v_lshlrev_b32_e32 v156, 16, v204
	v_and_b32_e32 v157, 0xffff0000, v204
	v_pk_mul_f32 v[64:65], v[64:65], v[156:157]
	v_lshlrev_b32_e32 v158, 16, v205
	v_and_b32_e32 v159, 0xffff0000, v205
	v_pk_mul_f32 v[66:67], v[66:67], v[158:159]
	v_lshlrev_b32_e32 v152, 16, v180
	v_and_b32_e32 v153, 0xffff0000, v180
	v_pk_add_f32 v[68:69], v[68:69], v[152:153]
	v_lshlrev_b32_e32 v154, 16, v181
	v_and_b32_e32 v155, 0xffff0000, v181
	v_pk_add_f32 v[70:71], v[70:71], v[154:155]
	v_lshlrev_b32_e32 v156, 16, v182
	v_and_b32_e32 v157, 0xffff0000, v182
	v_pk_add_f32 v[64:65], v[64:65], v[156:157]
	v_lshlrev_b32_e32 v158, 16, v183
	v_and_b32_e32 v159, 0xffff0000, v183
	v_pk_add_f32 v[66:67], v[66:67], v[158:159]
	v_cvt_pk_bf16_f32 v68, v68, v69
	v_cvt_pk_bf16_f32 v69, v70, v71
	v_cvt_pk_bf16_f32 v70, v64, v65
	v_cvt_pk_bf16_f32 v71, v66, v67
	global_load_dwordx4 v[202:205], v[160:161], off
	s_waitcnt vmcnt(4)
; __device__ __forceinline__ u32x4 pack8(const f32x4 a, const f32x4 b) { u32x4 w; w.x = cvt_pk_bf16(a[0], a[1]); w.y = cvt_pk_bf16(a[2], a[3]); w.z = cvt_pk_bf16(b[0], b[1]); w.w = cvt_pk_bf16(b[2], b[3]); return w; }
; #define EPI_ROWLOOP _Pragma("unroll") for (int ai = 0; ai < 2; ++ai) _Pragma("unroll") for (int m = 0; m < 4; ++m)
;     __device__ __forceinline__ void operator()(const f32x4 (&acc)[2][2][4][2], const Unit& u, int wr, int wc, int fr, int fq) const {
;     ...
;         EPI_ROWLOOP { const int r = row0 + ai * HALF + m * 16;
; #pragma unroll
;             for (int bj = 0; bj < 2; ++bj) { const int c = c0 + bj * HALF; f32x4 g0, g1; unpack8(*(const u32x4*)(GATES + (size_t)r * 2048 + (u.sel ? 1024 : 0) + c), g0, g1);
;                 f32x4 v0 = acc[ai][bj][m][0] * g0, v1 = acc[ai][bj][m][1] * g1;
;                 if (u.sel) { f32x4 t0, t1; unpack8(*(const u32x4*)(T + (size_t)r * 1024 + c), t0, t1); v0 += t0; v1 += t1; *(u32x4*)(MIX + (size_t)r * 1024 + c) = pack8(v0, v1); }
;                 else *(u32x4*)(T + (size_t)r * 1024 + c) = pack8(v0, v1); } }
	v_lshlrev_b32_e32 v152, 16, v206
	v_and_b32_e32 v153, 0xffff0000, v206
	v_pk_mul_f32 v[60:61], v[60:61], v[152:153]
	v_lshlrev_b32_e32 v154, 16, v207
	v_and_b32_e32 v155, 0xffff0000, v207
	v_pk_mul_f32 v[62:63], v[62:63], v[154:155]
	v_lshlrev_b32_e32 v156, 16, v208
	v_and_b32_e32 v157, 0xffff0000, v208
	v_pk_mul_f32 v[56:57], v[56:57], v[156:157]
	v_lshlrev_b32_e32 v158, 16, v209
	v_and_b32_e32 v159, 0xffff0000, v209
	v_pk_mul_f32 v[58:59], v[58:59], v[158:159]
	v_lshlrev_b32_e32 v152, 16, v184
	v_and_b32_e32 v153, 0xffff0000, v184
	v_pk_add_f32 v[60:61], v[60:61], v[152:153]
	v_lshlrev_b32_e32 v154, 16, v185
	v_and_b32_e32 v155, 0xffff0000, v185
	v_pk_add_f32 v[62:63], v[62:63], v[154:155]
	v_lshlrev_b32_e32 v156, 16, v186
	v_and_b32_e32 v157, 0xffff0000, v186
	v_pk_add_f32 v[56:57], v[56:57], v[156:157]
	v_lshlrev_b32_e32 v158, 16, v187
	v_and_b32_e32 v159, 0xffff0000, v187
	v_pk_add_f32 v[58:59], v[58:59], v[158:159]
	v_cvt_pk_bf16_f32 v60, v60, v61
	v_cvt_pk_bf16_f32 v61, v62, v63
	v_cvt_pk_bf16_f32 v62, v56, v57
	v_cvt_pk_bf16_f32 v63, v58, v59
	global_load_dwordx4 v[206:209], v[160:161], off offset:256
	v_lshl_add_u64 v[160:161], v[160:161], 0, s[6:7]
	s_waitcnt vmcnt(4)
	v_lshlrev_b32_e32 v152, 16, v210
	v_and_b32_e32 v153, 0xffff0000, v210
	v_pk_mul_f32 v[52:53], v[52:53], v[152:153]
	v_lshlrev_b32_e32 v154, 16, v211
	v_and_b32_e32 v155, 0xffff0000, v211
	v_pk_mul_f32 v[54:55], v[54:55], v[154:155]
	v_lshlrev_b32_e32 v156, 16, v212
	v_and_b32_e32 v157, 0xffff0000, v212
	v_pk_mul_f32 v[48:49], v[48:49], v[156:157]
	v_lshlrev_b32_e32 v158, 16, v213
	v_and_b32_e32 v159, 0xffff0000, v213
	v_pk_mul_f32 v[50:51], v[50:51], v[158:159]
	v_lshlrev_b32_e32 v152, 16, v188
	v_and_b32_e32 v153, 0xffff0000, v188
	v_pk_add_f32 v[52:53], v[52:53], v[152:153]
	v_lshlrev_b32_e32 v154, 16, v189
	v_and_b32_e32 v155, 0xffff0000, v189
	v_pk_add_f32 v[54:55], v[54:55], v[154:155]
	v_lshlrev_b32_e32 v156, 16, v190
	v_and_b32_e32 v157, 0xffff0000, v190
	v_pk_add_f32 v[48:49], v[48:49], v[156:157]
	v_lshlrev_b32_e32 v158, 16, v191
	v_and_b32_e32 v159, 0xffff0000, v191
	v_pk_add_f32 v[50:51], v[50:51], v[158:159]
	v_cvt_pk_bf16_f32 v52, v52, v53
	v_cvt_pk_bf16_f32 v53, v54, v55
	v_cvt_pk_bf16_f32 v54, v48, v49
	v_cvt_pk_bf16_f32 v55, v50, v51
	global_load_dwordx4 v[210:213], v[160:161], off
	s_waitcnt vmcnt(4)
	v_lshlrev_b32_e32 v152, 16, v214
	v_and_b32_e32 v153, 0xffff0000, v214
	v_pk_mul_f32 v[44:45], v[44:45], v[152:153]
	v_lshlrev_b32_e32 v154, 16, v215
	v_and_b32_e32 v155, 0xffff0000, v215
	v_pk_mul_f32 v[46:47], v[46:47], v[154:155]
	v_lshlrev_b32_e32 v156, 16, v216
	v_and_b32_e32 v157, 0xffff0000, v216
	v_pk_mul_f32 v[40:41], v[40:41], v[156:157]
	v_lshlrev_b32_e32 v158, 16, v217
	v_and_b32_e32 v159, 0xffff0000, v217
	v_pk_mul_f32 v[42:43], v[42:43], v[158:159]
	v_lshlrev_b32_e32 v152, 16, v192
	v_and_b32_e32 v153, 0xffff0000, v192
	v_pk_add_f32 v[44:45], v[44:45], v[152:153]
	v_lshlrev_b32_e32 v154, 16, v193
	v_and_b32_e32 v155, 0xffff0000, v193
	v_pk_add_f32 v[46:47], v[46:47], v[154:155]
	v_lshlrev_b32_e32 v156, 16, v194
	v_and_b32_e32 v157, 0xffff0000, v194
	v_pk_add_f32 v[40:41], v[40:41], v[156:157]
	v_lshlrev_b32_e32 v158, 16, v195
	v_and_b32_e32 v159, 0xffff0000, v195
	v_pk_add_f32 v[42:43], v[42:43], v[158:159]
	v_cvt_pk_bf16_f32 v44, v44, v45
	v_cvt_pk_bf16_f32 v45, v46, v47
	v_cvt_pk_bf16_f32 v46, v40, v41
	v_cvt_pk_bf16_f32 v47, v42, v43
	global_load_dwordx4 v[214:217], v[160:161], off offset:256
	s_waitcnt vmcnt(4)
	v_lshlrev_b32_e32 v152, 16, v218
	v_and_b32_e32 v153, 0xffff0000, v218
	v_pk_mul_f32 v[36:37], v[36:37], v[152:153]
	v_lshlrev_b32_e32 v154, 16, v219
	v_and_b32_e32 v155, 0xffff0000, v219
	v_pk_mul_f32 v[38:39], v[38:39], v[154:155]
	v_lshlrev_b32_e32 v156, 16, v220
	v_and_b32_e32 v157, 0xffff0000, v220
	v_pk_mul_f32 v[32:33], v[32:33], v[156:157]
	v_lshlrev_b32_e32 v158, 16, v221
	v_and_b32_e32 v159, 0xffff0000, v221
	v_pk_mul_f32 v[34:35], v[34:35], v[158:159]
	v_lshlrev_b32_e32 v152, 16, v196
	v_and_b32_e32 v153, 0xffff0000, v196
	v_pk_add_f32 v[36:37], v[36:37], v[152:153]
	v_lshlrev_b32_e32 v154, 16, v197
	v_and_b32_e32 v155, 0xffff0000, v197
	v_pk_add_f32 v[38:39], v[38:39], v[154:155]
	v_lshlrev_b32_e32 v156, 16, v198
	v_and_b32_e32 v157, 0xffff0000, v198
	v_pk_add_f32 v[32:33], v[32:33], v[156:157]
	v_lshlrev_b32_e32 v158, 16, v199
	v_and_b32_e32 v159, 0xffff0000, v199
	v_pk_add_f32 v[34:35], v[34:35], v[158:159]
	v_cvt_pk_bf16_f32 v36, v36, v37
	v_cvt_pk_bf16_f32 v37, v38, v39
	v_cvt_pk_bf16_f32 v38, v32, v33
	v_cvt_pk_bf16_f32 v39, v34, v35
	s_waitcnt vmcnt(3)
; __device__ __forceinline__ u32x4 pack8(const f32x4 a, const f32x4 b) { u32x4 w; w.x = cvt_pk_bf16(a[0], a[1]); w.y = cvt_pk_bf16(a[2], a[3]); w.z = cvt_pk_bf16(b[0], b[1]); w.w = cvt_pk_bf16(b[2], b[3]); return w; }
; #define EPI_ROWLOOP _Pragma("unroll") for (int ai = 0; ai < 2; ++ai) _Pragma("unroll") for (int m = 0; m < 4; ++m)
;     __device__ __forceinline__ void operator()(const f32x4 (&acc)[2][2][4][2], const Unit& u, int wr, int wc, int fr, int fq) const {
;     ...
;         EPI_ROWLOOP { const int r = row0 + ai * HALF + m * 16;
; #pragma unroll
;             for (int bj = 0; bj < 2; ++bj) { const int c = c0 + bj * HALF; f32x4 g0, g1; unpack8(*(const u32x4*)(GATES + (size_t)r * 2048 + (u.sel ? 1024 : 0) + c), g0, g1);
;                 f32x4 v0 = acc[ai][bj][m][0] * g0, v1 = acc[ai][bj][m][1] * g1;
;                 if (u.sel) { f32x4 t0, t1; unpack8(*(const u32x4*)(T + (size_t)r * 1024 + c), t0, t1); v0 += t0; v1 += t1; *(u32x4*)(MIX + (size_t)r * 1024 + c) = pack8(v0, v1); }
;                 else *(u32x4*)(T + (size_t)r * 1024 + c) = pack8(v0, v1); } }
	v_lshlrev_b32_e32 v152, 16, v222
	v_and_b32_e32 v153, 0xffff0000, v222
	v_pk_mul_f32 v[28:29], v[28:29], v[152:153]
	v_lshlrev_b32_e32 v154, 16, v223
	v_and_b32_e32 v155, 0xffff0000, v223
	v_pk_mul_f32 v[30:31], v[30:31], v[154:155]
	v_lshlrev_b32_e32 v156, 16, v224
	v_and_b32_e32 v157, 0xffff0000, v224
	v_pk_mul_f32 v[24:25], v[24:25], v[156:157]
	v_lshlrev_b32_e32 v158, 16, v225
	v_and_b32_e32 v159, 0xffff0000, v225
	v_pk_mul_f32 v[26:27], v[26:27], v[158:159]
	v_lshlrev_b32_e32 v152, 16, v202
	v_and_b32_e32 v153, 0xffff0000, v202
	v_pk_add_f32 v[28:29], v[28:29], v[152:153]
	v_lshlrev_b32_e32 v154, 16, v203
	v_and_b32_e32 v155, 0xffff0000, v203
	v_pk_add_f32 v[30:31], v[30:31], v[154:155]
	v_lshlrev_b32_e32 v156, 16, v204
	v_and_b32_e32 v157, 0xffff0000, v204
	v_pk_add_f32 v[24:25], v[24:25], v[156:157]
	v_lshlrev_b32_e32 v158, 16, v205
	v_and_b32_e32 v159, 0xffff0000, v205
	v_pk_add_f32 v[26:27], v[26:27], v[158:159]
	v_cvt_pk_bf16_f32 v28, v28, v29
	v_cvt_pk_bf16_f32 v29, v30, v31
	v_cvt_pk_bf16_f32 v30, v24, v25
	v_cvt_pk_bf16_f32 v31, v26, v27
	s_waitcnt vmcnt(2)
	v_lshlrev_b32_e32 v152, 16, v226
	v_and_b32_e32 v153, 0xffff0000, v226
	v_pk_mul_f32 v[20:21], v[20:21], v[152:153]
	v_lshlrev_b32_e32 v154, 16, v227
	v_and_b32_e32 v155, 0xffff0000, v227
	v_pk_mul_f32 v[22:23], v[22:23], v[154:155]
	v_lshlrev_b32_e32 v156, 16, v228
	v_and_b32_e32 v157, 0xffff0000, v228
	v_pk_mul_f32 v[16:17], v[16:17], v[156:157]
	v_lshlrev_b32_e32 v158, 16, v229
	v_and_b32_e32 v159, 0xffff0000, v229
	v_pk_mul_f32 v[18:19], v[18:19], v[158:159]
	v_lshlrev_b32_e32 v152, 16, v206
	v_and_b32_e32 v153, 0xffff0000, v206
	v_pk_add_f32 v[20:21], v[20:21], v[152:153]
	v_lshlrev_b32_e32 v154, 16, v207
	v_and_b32_e32 v155, 0xffff0000, v207
	v_pk_add_f32 v[22:23], v[22:23], v[154:155]
	v_lshlrev_b32_e32 v156, 16, v208
	v_and_b32_e32 v157, 0xffff0000, v208
	v_pk_add_f32 v[16:17], v[16:17], v[156:157]
	v_lshlrev_b32_e32 v158, 16, v209
	v_and_b32_e32 v159, 0xffff0000, v209
	v_pk_add_f32 v[18:19], v[18:19], v[158:159]
	v_cvt_pk_bf16_f32 v20, v20, v21
	v_cvt_pk_bf16_f32 v21, v22, v23
	v_cvt_pk_bf16_f32 v22, v16, v17
	v_cvt_pk_bf16_f32 v23, v18, v19
	s_waitcnt vmcnt(1)
	v_lshlrev_b32_e32 v152, 16, v230
	v_and_b32_e32 v153, 0xffff0000, v230
	v_pk_mul_f32 v[12:13], v[12:13], v[152:153]
	v_lshlrev_b32_e32 v154, 16, v231
	v_and_b32_e32 v155, 0xffff0000, v231
	v_pk_mul_f32 v[14:15], v[14:15], v[154:155]
	v_lshlrev_b32_e32 v156, 16, v232
	v_and_b32_e32 v157, 0xffff0000, v232
	v_pk_mul_f32 v[8:9], v[8:9], v[156:157]
	v_lshlrev_b32_e32 v158, 16, v233
	v_and_b32_e32 v159, 0xffff0000, v233
	v_pk_mul_f32 v[10:11], v[10:11], v[158:159]
	v_lshlrev_b32_e32 v152, 16, v210
	v_and_b32_e32 v153, 0xffff0000, v210
	v_pk_add_f32 v[12:13], v[12:13], v[152:153]
	v_lshlrev_b32_e32 v154, 16, v211
	v_and_b32_e32 v155, 0xffff0000, v211
	v_pk_add_f32 v[14:15], v[14:15], v[154:155]
	v_lshlrev_b32_e32 v156, 16, v212
	v_and_b32_e32 v157, 0xffff0000, v212
	v_pk_add_f32 v[8:9], v[8:9], v[156:157]
	v_lshlrev_b32_e32 v158, 16, v213
	v_and_b32_e32 v159, 0xffff0000, v213
	v_pk_add_f32 v[10:11], v[10:11], v[158:159]
	v_cvt_pk_bf16_f32 v12, v12, v13
	v_cvt_pk_bf16_f32 v13, v14, v15
	v_cvt_pk_bf16_f32 v14, v8, v9
	v_cvt_pk_bf16_f32 v15, v10, v11
	s_waitcnt vmcnt(0)
	v_lshlrev_b32_e32 v152, 16, v236
	v_and_b32_e32 v153, 0xffff0000, v236
	v_pk_mul_f32 v[4:5], v[4:5], v[152:153]
	v_lshlrev_b32_e32 v154, 16, v237
	v_and_b32_e32 v155, 0xffff0000, v237
	v_pk_mul_f32 v[6:7], v[6:7], v[154:155]
	v_lshlrev_b32_e32 v156, 16, v238
	v_and_b32_e32 v157, 0xffff0000, v238
	v_pk_mul_f32 v[0:1], v[0:1], v[156:157]
	v_lshlrev_b32_e32 v158, 16, v239
	v_and_b32_e32 v159, 0xffff0000, v239
	v_pk_mul_f32 v[2:3], v[2:3], v[158:159]
	v_lshlrev_b32_e32 v152, 16, v214
	v_and_b32_e32 v153, 0xffff0000, v214
	v_pk_add_f32 v[4:5], v[4:5], v[152:153]
	v_lshlrev_b32_e32 v154, 16, v215
	v_and_b32_e32 v155, 0xffff0000, v215
	v_pk_add_f32 v[6:7], v[6:7], v[154:155]
	v_lshlrev_b32_e32 v156, 16, v216
	v_and_b32_e32 v157, 0xffff0000, v216
	v_pk_add_f32 v[0:1], v[0:1], v[156:157]
	v_lshlrev_b32_e32 v158, 16, v217
	v_and_b32_e32 v159, 0xffff0000, v217
	v_pk_add_f32 v[2:3], v[2:3], v[158:159]
	v_cvt_pk_bf16_f32 v4, v4, v5
	v_cvt_pk_bf16_f32 v5, v6, v7
	v_cvt_pk_bf16_f32 v6, v0, v1
	v_cvt_pk_bf16_f32 v7, v2, v3
	s_mov_b64 s[6:7], 0x8000
	s_mov_b64 s[52:53], 0x28000
	global_store_dwordx4 v[164:165], v[120:123], off
	global_store_dwordx4 v[164:165], v[116:119], off offset:256
	v_lshl_add_u64 v[164:165], v[164:165], 0, s[6:7]
	global_store_dwordx4 v[164:165], v[108:111], off
	global_store_dwordx4 v[164:165], v[100:103], off offset:256
	v_lshl_add_u64 v[164:165], v[164:165], 0, s[6:7]
	global_store_dwordx4 v[164:165], v[92:95], off
	global_store_dwordx4 v[164:165], v[84:87], off offset:256
	v_lshl_add_u64 v[164:165], v[164:165], 0, s[6:7]
	global_store_dwordx4 v[164:165], v[76:79], off
	global_store_dwordx4 v[164:165], v[68:71], off offset:256
	v_lshl_add_u64 v[164:165], v[164:165], 0, s[52:53]
	global_store_dwordx4 v[164:165], v[60:63], off
	global_store_dwordx4 v[164:165], v[52:55], off offset:256
	v_lshl_add_u64 v[164:165], v[164:165], 0, s[6:7]
	global_store_dwordx4 v[164:165], v[44:47], off
	global_store_dwordx4 v[164:165], v[36:39], off offset:256
	v_lshl_add_u64 v[164:165], v[164:165], 0, s[6:7]
	global_store_dwordx4 v[164:165], v[28:31], off
	global_store_dwordx4 v[164:165], v[20:23], off offset:256
	v_lshl_add_u64 v[164:165], v[164:165], 0, s[6:7]
	global_store_dwordx4 v[164:165], v[12:15], off
	s_and_b64 vcc, exec, s[4:5]
	s_mov_b64 s[4:5], -1
	global_store_dwordx4 v[164:165], v[4:7], off offset:256
	s_branch .Lp5_done
